# idle partner polling adaptive: s_sleep 127 for the first 98 polls (bulk of the scan) then s_sleep 16, on v40/v41
# baseline (speedup 1.0000x reference)
.Lmix_sec_wait:
	global_load_dword v3, v2, s[12:13] sc1
	s_waitcnt vmcnt(0)
	v_readfirstlane_b32 s8, v3
	s_lshr_b32 s8, s8, 24
	s_cmp_lg_u32 s8, 0
	s_cbranch_scc1 .Lmix_sec_done
	s_cmp_lt_u32 s2, 98
	s_cbranch_scc1 .Lmix_sec_long
	s_sleep 16
	s_branch .Lmix_sec_next
.Lmix_sec_long:
	s_sleep 127
.Lmix_sec_next:
	s_add_i32 s2, s2, 1
	s_cmp_lt_u32 s2, 0x4000
	s_cbranch_scc1 .Lmix_sec_wait
